# sp4 dilated-attention path: replace four 15-deep cmp/cndmask select chains by 12 cndmask on existing lane masks (plus nt stores for proj output)
# speedup vs baseline: 1.1714x; 1.0033x over previous
; #define LAS __attribute__((address_space(3)))
; #define MFMA32(a, b, c) __builtin_amdgcn_mfma_f32_32x32x16_bf16((a), (b), (c), 0, 0, 0)
; DI void attn_compute_sp4(const bf16x8 (&qf)[4], const bf16x8 (&kf)[4], const bf16x8 (&vf)[2][2], int kt, int d00, const float* lut, AttnSt& st, int win, int dmask) {
;     const int s0 = kt * 32;
;     f32x16 sx;
; #pragma unroll
;     for (int i = 0; i < 16; ++i) sx[i] = 0.f;
; #pragma unroll
;     for (int ks = 0; ks < 4; ++ks) sx = MFMA32(kf[ks], qf[ks], sx);
;     const int d0 = d00 - s0, e = d0 & 3;
;     const bool e0 = (e == 0), e1 = (e == 1), e2 = (e == 2);
;     const LAS float* lb = (const LAS float*)lut + (d0 - e - 20);
;     float sv[4]; float mx = NEGF;
; #pragma unroll
;     for (int g = 0; g < 4; ++g) {
;         const float x = e0 ? sx[4 * g] : (e1 ? sx[4 * g + 1] : (e2 ? sx[4 * g + 2] : sx[4 * g + 3]));
;         const int dist = d0 - (16 * (g >> 1) + 4 * (g & 1)) - e;
;         const bool v = ((unsigned)dist <= (unsigned)win) && ((dist & dmask) == 0);
;         const float bias = lb[20 - (16 * (g >> 1) + 4 * (g & 1))];
;         float sc = fmaf(x, SC2, bias);
;         sc = v ? sc : NEGF;
;         sv[g] = sc; mx = fmaxf(mx, sc);
;     }
;     mx = fmaxf(mx, __shfl_xor(mx, 32));
;     const float mnew = fmaxf(st.m, mx);
;     const float msafe = (mnew > -1e29f) ? mnew : 0.f;
;     if (__ballot(mnew > st.m) != 0ull) {
;         const float alpha = __builtin_amdgcn_exp2f(st.m - msafe);
;         st.l *= alpha; st.m = mnew;
; #pragma unroll
;         for (int i = 0; i < 16; ++i) { st.o0[i] *= alpha; st.o1[i] *= alpha; }
;     }
.LBB0_285:
	s_andn2_b64 vcc, exec, s[4:5]
	s_mov_b64 s[46:47], -1
	s_cbranch_vccnz .LBB0_289
	s_waitcnt lgkmcnt(0)
	v_mfma_f32_32x32x16_bf16 v[34:49], v[106:109], v[78:81], 0
	ds_read2_b32 v[50:51], v152 offset0:16 offset1:20
	ds_read2_b32 v[60:61], v152 offset1:4
	v_add_u32_e32 v52, v163, v151
	v_add_u32_e32 v53, 0x98, v52
	v_mov_b32_e32 v172, v150
	v_mov_b32_e32 v169, v153
	v_mfma_f32_32x32x16_bf16 v[34:49], v[110:113], v[74:77], v[34:49]
	v_mfma_f32_32x32x16_bf16 v[34:49], v[102:105], v[70:73], v[34:49]
	v_mfma_f32_32x32x16_bf16 v[34:49], v[98:101], v[66:69], v[34:49]
	s_nop 11
	v_cndmask_b32_e64 v54, v37, v36, s[38:39]
	v_cndmask_b32_e64 v56, v41, v40, s[38:39]
	v_cndmask_b32_e64 v57, v45, v44, s[38:39]
	v_cndmask_b32_e64 v58, v49, v48, s[38:39]
	v_cndmask_b32_e64 v54, v54, v35, s[40:41]
	v_cndmask_b32_e64 v56, v56, v39, s[40:41]
	v_cndmask_b32_e64 v57, v57, v43, s[40:41]
	v_cndmask_b32_e64 v58, v58, v47, s[40:41]
	v_cndmask_b32_e64 v54, v54, v34, s[42:43]
	v_cndmask_b32_e64 v56, v56, v38, s[42:43]
	v_cndmask_b32_e64 v57, v57, v42, s[42:43]
	v_cndmask_b32_e64 v58, v58, v46, s[42:43]
	s_waitcnt lgkmcnt(0)
	v_fmamk_f32 v51, v54, 0x3e38aa3b, v51
	v_cmp_gt_u32_e32 vcc, s31, v53
	v_add_u32_e32 v53, 0x94, v52
	s_nop 0
	v_cndmask_b32_e32 v170, v239, v51, vcc
	v_add_u32_e32 v55, 0x88, v52
	v_fmac_f32_e32 v50, 0x3e38aa3b, v56
	v_cmp_gt_u32_e32 vcc, s31, v53
	s_nop 1
	v_cndmask_b32_e32 v171, v239, v50, vcc
	v_max3_f32 v53, v170, s30, v171
	v_fmamk_f32 v61, v57, 0x3e38aa3b, v61
	v_cmp_gt_u32_e32 vcc, s31, v55
	s_nop 1
	v_cndmask_b32_e32 v173, v239, v61, vcc
	v_add_u32_e32 v35, 0x84, v52
	v_fmac_f32_e32 v60, 0x3e38aa3b, v58
	v_cmp_gt_u32_e32 vcc, s31, v35
	s_nop 1
	v_cndmask_b32_e32 v174, v239, v60, vcc
	v_max3_f32 v34, v53, v173, v174
	ds_bpermute_b32 v35, v160, v34
	v_mov_b64_e32 v[64:65], v[32:33]
	v_mov_b64_e32 v[62:63], v[30:31]
	v_mov_b64_e32 v[60:61], v[28:29]
	v_mov_b64_e32 v[58:59], v[26:27]
	s_waitcnt lgkmcnt(0)
	v_max3_f32 v176, v153, v34, v35
	v_cmp_lt_f32_e32 vcc, s12, v176
	v_mov_b64_e32 v[48:49], v[16:17]
	v_mov_b64_e32 v[56:57], v[24:25]
	v_cndmask_b32_e32 v175, 0, v176, vcc
	v_cmp_gt_f32_e32 vcc, v176, v153
	v_mov_b64_e32 v[54:55], v[22:23]
	v_mov_b64_e32 v[52:53], v[20:21]
	v_mov_b64_e32 v[50:51], v[18:19]
	v_mov_b64_e32 v[46:47], v[14:15]
	v_mov_b64_e32 v[44:45], v[12:13]
	v_mov_b64_e32 v[42:43], v[10:11]
	v_mov_b64_e32 v[40:41], v[8:9]
	v_mov_b64_e32 v[38:39], v[6:7]
	v_mov_b64_e32 v[36:37], v[4:5]
	v_mov_b64_e32 v[34:35], v[2:3]
	s_cbranch_vccz .LBB0_288
	v_sub_f32_e32 v34, v153, v175
	v_exp_f32_e32 v50, v34
	v_mov_b32_e32 v169, v176
	v_mul_f32_e32 v172, v150, v50
	v_pk_mul_f32 v[48:49], v[16:17], v[50:51] op_sel_hi:[1,0]
	v_pk_mul_f32 v[46:47], v[14:15], v[50:51] op_sel_hi:[1,0]
	v_pk_mul_f32 v[44:45], v[12:13], v[50:51] op_sel_hi:[1,0]
	v_pk_mul_f32 v[42:43], v[10:11], v[50:51] op_sel_hi:[1,0]
	v_pk_mul_f32 v[40:41], v[8:9], v[50:51] op_sel_hi:[1,0]
	v_pk_mul_f32 v[38:39], v[6:7], v[50:51] op_sel_hi:[1,0]
	v_pk_mul_f32 v[36:37], v[4:5], v[50:51] op_sel_hi:[1,0]
	v_pk_mul_f32 v[34:35], v[2:3], v[50:51] op_sel_hi:[1,0]
	v_pk_mul_f32 v[64:65], v[32:33], v[50:51] op_sel_hi:[1,0]
	v_pk_mul_f32 v[62:63], v[30:31], v[50:51] op_sel_hi:[1,0]
	v_pk_mul_f32 v[60:61], v[28:29], v[50:51] op_sel_hi:[1,0]
	v_pk_mul_f32 v[58:59], v[26:27], v[50:51] op_sel_hi:[1,0]
	v_pk_mul_f32 v[56:57], v[24:25], v[50:51] op_sel_hi:[1,0]
	v_pk_mul_f32 v[54:55], v[22:23], v[50:51] op_sel_hi:[1,0]
	v_pk_mul_f32 v[52:53], v[20:21], v[50:51] op_sel_hi:[1,0]
	v_pk_mul_f32 v[50:51], v[18:19], v[50:51] op_sel_hi:[1,0]

; #define LAS __attribute__((address_space(3)))
; #define MFMA32(a, b, c) __builtin_amdgcn_mfma_f32_32x32x16_bf16((a), (b), (c), 0, 0, 0)
; DI void attn_compute_sp4(const bf16x8 (&qf)[4], const bf16x8 (&kf)[4], const bf16x8 (&vf)[2][2], int kt, int d00, const float* lut, AttnSt& st, int win, int dmask) {
;     const int s0 = kt * 32;
;     f32x16 sx;
; #pragma unroll
;     for (int i = 0; i < 16; ++i) sx[i] = 0.f;
; #pragma unroll
;     for (int ks = 0; ks < 4; ++ks) sx = MFMA32(kf[ks], qf[ks], sx);
;     const int d0 = d00 - s0, e = d0 & 3;
;     const bool e0 = (e == 0), e1 = (e == 1), e2 = (e == 2);
;     const LAS float* lb = (const LAS float*)lut + (d0 - e - 20);
;     float sv[4]; float mx = NEGF;
; #pragma unroll
;     for (int g = 0; g < 4; ++g) {
;         const float x = e0 ? sx[4 * g] : (e1 ? sx[4 * g + 1] : (e2 ? sx[4 * g + 2] : sx[4 * g + 3]));
;         const int dist = d0 - (16 * (g >> 1) + 4 * (g & 1)) - e;
;         const bool v = ((unsigned)dist <= (unsigned)win) && ((dist & dmask) == 0);
;         const float bias = lb[20 - (16 * (g >> 1) + 4 * (g & 1))];
;         float sc = fmaf(x, SC2, bias);
;         sc = v ? sc : NEGF;
;         sv[g] = sc; mx = fmaxf(mx, sc);
;     }
;     mx = fmaxf(mx, __shfl_xor(mx, 32));
;     const float mnew = fmaxf(st.m, mx);
;     const float msafe = (mnew > -1e29f) ? mnew : 0.f;
;     if (__ballot(mnew > st.m) != 0ull) {
;         const float alpha = __builtin_amdgcn_exp2f(st.m - msafe);
;         st.l *= alpha; st.m = mnew;
; #pragma unroll
;         for (int i = 0; i < 16; ++i) { st.o0[i] *= alpha; st.o1[i] *= alpha; }
;     }
.LBB0_304:
	s_andn2_b64 vcc, exec, s[4:5]
	s_mov_b64 s[46:47], -1
	s_cbranch_vccnz .LBB0_308
	s_waitcnt lgkmcnt(0)
	v_mfma_f32_32x32x16_bf16 v[2:17], v[106:109], v[78:81], 0
	ds_read2_b32 v[50:51], v171 offset0:16 offset1:20
	ds_read2_b32 v[60:61], v171 offset1:4
	v_add_u32_e32 v52, v163, v170
	v_add_u32_e32 v53, 0x98, v52
	v_mov_b32_e32 v176, v149
	v_mov_b32_e32 v173, v172
	v_mfma_f32_32x32x16_bf16 v[2:17], v[110:113], v[74:77], v[2:17]
	v_mfma_f32_32x32x16_bf16 v[2:17], v[102:105], v[70:73], v[2:17]
	v_mfma_f32_32x32x16_bf16 v[2:17], v[98:101], v[66:69], v[2:17]
	s_nop 11
	v_cndmask_b32_e64 v54, v5, v4, s[38:39]
	v_cndmask_b32_e64 v56, v9, v8, s[38:39]
	v_cndmask_b32_e64 v57, v13, v12, s[38:39]
	v_cndmask_b32_e64 v58, v17, v16, s[38:39]
	v_cndmask_b32_e64 v54, v54, v3, s[40:41]
	v_cndmask_b32_e64 v56, v56, v7, s[40:41]
	v_cndmask_b32_e64 v57, v57, v11, s[40:41]
	v_cndmask_b32_e64 v58, v58, v15, s[40:41]
	v_cndmask_b32_e64 v54, v54, v2, s[42:43]
	v_cndmask_b32_e64 v56, v56, v6, s[42:43]
	v_cndmask_b32_e64 v57, v57, v10, s[42:43]
	v_cndmask_b32_e64 v58, v58, v14, s[42:43]
	s_waitcnt lgkmcnt(0)
	v_fmamk_f32 v51, v54, 0x3e38aa3b, v51
	v_cmp_gt_u32_e32 vcc, s31, v53
	v_add_u32_e32 v53, 0x94, v52
	s_nop 0
	v_cndmask_b32_e32 v174, v239, v51, vcc
	v_add_u32_e32 v55, 0x88, v52
	v_fmac_f32_e32 v50, 0x3e38aa3b, v56
	v_cmp_gt_u32_e32 vcc, s31, v53
	s_nop 1
	v_cndmask_b32_e32 v175, v239, v50, vcc
	v_max3_f32 v53, v174, s30, v175
	v_fmamk_f32 v61, v57, 0x3e38aa3b, v61
	v_cmp_gt_u32_e32 vcc, s31, v55
	s_nop 1
	v_cndmask_b32_e32 v177, v239, v61, vcc
	v_add_u32_e32 v3, 0x84, v52
	v_fmac_f32_e32 v60, 0x3e38aa3b, v58
	v_cmp_gt_u32_e32 vcc, s31, v3
	s_nop 1
	v_cndmask_b32_e32 v178, v239, v60, vcc
	v_max3_f32 v2, v53, v177, v178
	ds_bpermute_b32 v3, v160, v2
	v_mov_b64_e32 v[64:65], v[48:49]
	v_mov_b64_e32 v[62:63], v[46:47]
	v_mov_b64_e32 v[60:61], v[44:45]
	v_mov_b64_e32 v[58:59], v[42:43]
	s_waitcnt lgkmcnt(0)
	v_max3_f32 v180, v172, v2, v3
	v_cmp_lt_f32_e32 vcc, s12, v180
	v_mov_b64_e32 v[2:3], v[18:19]
	v_mov_b64_e32 v[4:5], v[20:21]
	v_cndmask_b32_e32 v179, 0, v180, vcc
	v_cmp_gt_f32_e32 vcc, v180, v172
	v_mov_b64_e32 v[6:7], v[22:23]
	v_mov_b64_e32 v[8:9], v[24:25]
	v_mov_b64_e32 v[10:11], v[26:27]
	v_mov_b64_e32 v[12:13], v[28:29]
	v_mov_b64_e32 v[14:15], v[30:31]
	v_mov_b64_e32 v[16:17], v[32:33]
	v_mov_b64_e32 v[56:57], v[40:41]
	v_mov_b64_e32 v[54:55], v[38:39]
	v_mov_b64_e32 v[52:53], v[36:37]
	v_mov_b64_e32 v[50:51], v[34:35]
	s_cbranch_vccz .LBB0_307
	v_sub_f32_e32 v2, v172, v179
	v_exp_f32_e32 v2, v2
	v_mov_b32_e32 v173, v180
	v_mul_f32_e32 v176, v149, v2
	v_pk_mul_f32 v[64:65], v[48:49], v[2:3] op_sel_hi:[1,0]
	v_pk_mul_f32 v[62:63], v[46:47], v[2:3] op_sel_hi:[1,0]
	v_pk_mul_f32 v[60:61], v[44:45], v[2:3] op_sel_hi:[1,0]
	v_pk_mul_f32 v[58:59], v[42:43], v[2:3] op_sel_hi:[1,0]
	v_pk_mul_f32 v[56:57], v[40:41], v[2:3] op_sel_hi:[1,0]
	v_pk_mul_f32 v[54:55], v[38:39], v[2:3] op_sel_hi:[1,0]
	v_pk_mul_f32 v[52:53], v[36:37], v[2:3] op_sel_hi:[1,0]
	v_pk_mul_f32 v[50:51], v[34:35], v[2:3] op_sel_hi:[1,0]
	v_pk_mul_f32 v[16:17], v[32:33], v[2:3] op_sel_hi:[1,0]
	v_pk_mul_f32 v[14:15], v[30:31], v[2:3] op_sel_hi:[1,0]
	v_pk_mul_f32 v[12:13], v[28:29], v[2:3] op_sel_hi:[1,0]
	v_pk_mul_f32 v[10:11], v[26:27], v[2:3] op_sel_hi:[1,0]
	v_pk_mul_f32 v[8:9], v[24:25], v[2:3] op_sel_hi:[1,0]
	v_pk_mul_f32 v[6:7], v[22:23], v[2:3] op_sel_hi:[1,0]
	v_pk_mul_f32 v[4:5], v[20:21], v[2:3] op_sel_hi:[1,0]
	v_pk_mul_f32 v[2:3], v[18:19], v[2:3] op_sel_hi:[1,0]
